# attention block selection: combined importance computed once per token-block into LDS, rank counts from one batched row read (same comparisons and tie-break)
# speedup vs baseline: 1.0047x; 1.0043x over previous
; #define LAS __attribute__((address_space(3)))
; __device__ __forceinline__ float bf2f(unsigned short b) { return __uint_as_float(((unsigned)b) << 16); }
; __device__ __forceinline__ float sigm(float x) { return __builtin_amdgcn_rcpf(1.0f + __expf(-x)); }
; __device__ __forceinline__ void nsa_mfma_phase(const bf16* z, const bf16* kch, const bf16* kcl, const bf16* vct, const bf16* vst, const bf16* vwt, const float* biasTab, bf16* oc,
;                                                LAS unsigned char* lds, int tid0, int vcu, int G) {
;     ...
;             l += __shfl_xor(l, 32);
;             const float invl = l > 0.f ? 1.0f / l : 0.f;
;             { const float g0 = sigm(bf2f(z[row * ZP + C_NG + head])) * invl;
; #pragma unroll
;               for (int r = 0; r < 16; ++r) { tot[0][r] *= g0; tot[1][r] *= g0; } }
;             if (qb >= 16) {
;                 if (hi_p == 0) invlS[hh * 64 + iq] = invl;
;                 __syncthreads();
;                 { const int tok = tid >> 3, jg = tid & 7; unsigned bits = 0u; const LAS float* i0 = impH + tok * 33;
;                   const float w0 = invlS[tok], w1 = invlS[64 + tok], w2 = invlS[128 + tok], w3 = invlS[192 + tok];
; #pragma unroll 1
;                   for (int jj = 0; jj < 4; ++jj) { const int j = jg * 4 + jj; if (j < 1 || j > qb - 2) continue;
;                       const float x = (i0[j] * w0 + i0[64 * 33 + j] * w1) + (i0[2 * 64 * 33 + j] * w2 + i0[3 * 64 * 33 + j] * w3); int cnt = 0;
.LBB0_824:
	ds_bpermute_b32 v36, v238, v74
	s_lshl_b32 s4, 2, s48
	s_add_i32 s10, s4, -1
	s_cmp_lt_u32 s48, 16
	s_mov_b32 s37, s69
	s_waitcnt lgkmcnt(0)
	v_add_f32_e32 v38, v74, v36
	v_div_scale_f32 v36, s[4:5], v38, v38, 1.0
	v_rcp_f32_e32 v37, v36
	v_div_scale_f32 v39, vcc, 1.0, v38, 1.0
	s_cselect_b32 s4, s10, 0
	v_fma_f32 v40, -v36, v37, 1.0
	v_fmac_f32_e32 v37, v40, v37
	v_mul_f32_e32 v40, v39, v37
	v_fma_f32 v41, -v36, v40, v39
	v_fmac_f32_e32 v40, v41, v37
	v_fma_f32 v36, -v36, v40, v39
	s_lshl_b32 s36, s56, 1
	v_div_fmas_f32 v39, v36, v37, v40
	v_lshl_add_u64 v[36:37], v[166:167], 0, s[36:37]
	v_add_co_u32_e32 v36, vcc, 0x5000, v36
	v_mov_b32_e32 v156, s4
	s_nop 0
	v_addc_co_u32_e32 v37, vcc, 0, v37, vcc
	global_load_ushort v240, v[36:37], off offset:2048
	v_div_fixup_f32 v36, v39, v38, 1.0
	v_cmp_lt_f32_e32 vcc, 0, v38
	s_nop 1
	v_cndmask_b32_e32 v239, 0, v36, vcc
	s_and_b64 vcc, exec, s[14:15]
	s_cbranch_vccz .LBB0_841
	s_and_saveexec_b64 s[4:5], s[8:9]
	v_lshl_add_u32 v36, v236, 2, s58
	ds_write_b32 v36, v239
	s_or_b64 exec, exec, s[4:5]
	v_ashrrev_i32_e32 v68, 3, v158
	v_and_b32_e32 v57, 7, v158
	v_lshlrev_b32_e32 v55, 2, v68
	v_mul_lo_u32 v52, v68, s97
	v_add_u32_e32 v38, 0x19d00, v55
	v_lshl_add_u32 v56, v57, 4, v52
	s_add_i32 s37, s48, -2
	s_add_i32 s50, s48, -1
	s_waitcnt lgkmcnt(0)
	s_barrier
	ds_read2st64_b32 v[36:37], v38 offset1:1
	ds_read2st64_b32 v[38:39], v38 offset0:2 offset1:3
	v_add_u32_e32 v60, 0x11800, v56
	v_add_u32_e32 v61, 0x13900, v56
	v_add_u32_e32 v62, 0x15a00, v56
	v_add_u32_e32 v63, 0x17b00, v56
	ds_read2_b32 v[40:41], v60 offset1:1
	ds_read2_b32 v[42:43], v60 offset0:2 offset1:3
	ds_read2_b32 v[44:45], v61 offset1:1
	ds_read2_b32 v[46:47], v61 offset0:2 offset1:3
	ds_read2_b32 v[48:49], v62 offset1:1
	ds_read2_b32 v[50:51], v62 offset0:2 offset1:3
	ds_read2_b32 v[64:65], v63 offset1:1
	ds_read2_b32 v[66:67], v63 offset0:2 offset1:3
	v_add_u32_e32 v59, 0x1a100, v56
	v_add_u32_e32 v53, 0x1a100, v52
	v_lshlrev_b32_e32 v112, 2, v57
	v_lshl_or_b32 v113, v57, 2, 1
	v_lshl_or_b32 v114, v57, 2, 2
	v_lshl_or_b32 v115, v57, 2, 3
	s_waitcnt lgkmcnt(0)
	v_mul_f32_e32 v72, v37, v44
	v_mul_f32_e32 v116, v39, v64
	v_mul_f32_e32 v73, v37, v45
	v_mul_f32_e32 v117, v39, v65
	v_mul_f32_e32 v74, v37, v46
	v_mul_f32_e32 v118, v39, v66
	v_mul_f32_e32 v75, v37, v47
	v_mul_f32_e32 v119, v39, v67
	v_fmac_f32_e32 v72, v36, v40
	v_fmac_f32_e32 v116, v38, v48
	v_fmac_f32_e32 v73, v36, v41
	v_fmac_f32_e32 v117, v38, v49
	v_fmac_f32_e32 v74, v36, v42
	v_fmac_f32_e32 v118, v38, v50
	v_fmac_f32_e32 v75, v36, v43
	v_fmac_f32_e32 v119, v38, v51
	v_add_f32_e32 v72, v72, v116
	v_add_f32_e32 v73, v73, v117
	v_add_f32_e32 v74, v74, v118
	v_add_f32_e32 v75, v75, v119
	ds_write2_b32 v59, v72, v73 offset1:1
	ds_write2_b32 v59, v74, v75 offset0:2 offset1:3
	ds_read2_b32 v[76:77], v53 offset0:0 offset1:1
	ds_read2_b32 v[78:79], v53 offset0:2 offset1:3
	ds_read2_b32 v[80:81], v53 offset0:4 offset1:5
	ds_read2_b32 v[82:83], v53 offset0:6 offset1:7
	ds_read2_b32 v[84:85], v53 offset0:8 offset1:9
	ds_read2_b32 v[86:87], v53 offset0:10 offset1:11
	ds_read2_b32 v[88:89], v53 offset0:12 offset1:13
	ds_read2_b32 v[90:91], v53 offset0:14 offset1:15
	ds_read2_b32 v[92:93], v53 offset0:16 offset1:17
	ds_read2_b32 v[94:95], v53 offset0:18 offset1:19
	ds_read2_b32 v[96:97], v53 offset0:20 offset1:21
	ds_read2_b32 v[98:99], v53 offset0:22 offset1:23
	ds_read2_b32 v[100:101], v53 offset0:24 offset1:25
	ds_read2_b32 v[102:103], v53 offset0:26 offset1:27
	ds_read2_b32 v[104:105], v53 offset0:28 offset1:29
	ds_read2_b32 v[106:107], v53 offset0:30 offset1:31
	v_mov_b32_e32 v108, 0
	v_mov_b32_e32 v109, 0
	v_mov_b32_e32 v110, 0
	v_mov_b32_e32 v111, 0
	v_mov_b32_e32 v58, 0
	s_waitcnt lgkmcnt(0)
	s_mov_b32 s10, 0xfefefefe
	s_mov_b32 s11, s10
	v_cmp_gt_f32_e32 vcc, v77, v72
	v_cmp_ge_f32_e64 s[38:39], v77, v72
	v_cmp_gt_f32_e64 s[14:15], v77, v73
	v_cmp_ge_f32_e64 s[40:41], v77, v73
	v_cmp_ge_f32_e64 s[16:17], v77, v74
	v_cmp_ge_f32_e64 s[18:19], v77, v75
	s_and_b64 s[38:39], s[38:39], s[10:11]
	s_or_b64 vcc, vcc, s[38:39]
	s_and_b64 s[40:41], s[40:41], s[10:11]
	s_or_b64 s[14:15], s[14:15], s[40:41]
	v_addc_co_u32_e32 v108, vcc, 0, v108, vcc
	v_addc_co_u32_e64 v109, s[14:15], 0, v109, s[14:15]
	v_addc_co_u32_e64 v110, s[16:17], 0, v110, s[16:17]
	v_addc_co_u32_e64 v111, s[18:19], 0, v111, s[18:19]
	s_mov_b32 s10, 0xfefefefe
	s_mov_b32 s11, s10
	v_cmp_gt_f32_e32 vcc, v78, v72
	v_cmp_ge_f32_e64 s[38:39], v78, v72
	v_cmp_gt_f32_e64 s[14:15], v78, v73
	v_cmp_ge_f32_e64 s[40:41], v78, v73
	v_cmp_gt_f32_e64 s[16:17], v78, v74
	v_cmp_ge_f32_e64 s[52:53], v78, v74
	v_cmp_ge_f32_e64 s[18:19], v78, v75
	s_and_b64 s[38:39], s[38:39], s[10:11]
	s_or_b64 vcc, vcc, s[38:39]
	s_and_b64 s[40:41], s[40:41], s[10:11]
	s_or_b64 s[14:15], s[14:15], s[40:41]
	s_and_b64 s[52:53], s[52:53], s[10:11]
	s_or_b64 s[16:17], s[16:17], s[52:53]
	v_addc_co_u32_e32 v108, vcc, 0, v108, vcc
	v_addc_co_u32_e64 v109, s[14:15], 0, v109, s[14:15]
	v_addc_co_u32_e64 v110, s[16:17], 0, v110, s[16:17]
	v_addc_co_u32_e64 v111, s[18:19], 0, v111, s[18:19]
	s_mov_b32 s10, 0xfefefefe
	s_mov_b32 s11, s10
	v_cmp_gt_f32_e32 vcc, v79, v72
	v_cmp_ge_f32_e64 s[38:39], v79, v72
	v_cmp_gt_f32_e64 s[14:15], v79, v73
	v_cmp_ge_f32_e64 s[40:41], v79, v73
	v_cmp_gt_f32_e64 s[16:17], v79, v74
	v_cmp_ge_f32_e64 s[52:53], v79, v74
	v_cmp_gt_f32_e64 s[18:19], v79, v75
	v_cmp_ge_f32_e64 s[62:63], v79, v75
	s_and_b64 s[38:39], s[38:39], s[10:11]
	s_or_b64 vcc, vcc, s[38:39]
	s_and_b64 s[40:41], s[40:41], s[10:11]
	s_or_b64 s[14:15], s[14:15], s[40:41]
	s_and_b64 s[52:53], s[52:53], s[10:11]
	s_or_b64 s[16:17], s[16:17], s[52:53]
; __device__ __forceinline__ void nsa_mfma_phase(const bf16* z, const bf16* kch, const bf16* kcl, const bf16* vct, const bf16* vst, const bf16* vwt, const float* biasTab, bf16* oc,
;                                                LAS unsigned char* lds, int tid0, int vcu, int G) {
;     ...
;                   for (int jj = 0; jj < 4; ++jj) { const int j = jg * 4 + jj; if (j < 1 || j > qb - 2) continue;
;                       const float x = (i0[j] * w0 + i0[64 * 33 + j] * w1) + (i0[2 * 64 * 33 + j] * w2 + i0[3 * 64 * 33 + j] * w3); int cnt = 0;
;                       for (int j2 = 1; j2 <= qb - 2; ++j2) { const float y = (i0[j2] * w0 + i0[64 * 33 + j2] * w1) + (i0[2 * 64 * 33 + j2] * w2 + i0[3 * 64 * 33 + j2] * w3); cnt += (y > x || (y == x && j2 < j)) ? 1 : 0; }
	s_and_b64 s[62:63], s[62:63], s[10:11]
	s_or_b64 s[18:19], s[18:19], s[62:63]
	v_addc_co_u32_e32 v108, vcc, 0, v108, vcc
	v_addc_co_u32_e64 v109, s[14:15], 0, v109, s[14:15]
	v_addc_co_u32_e64 v110, s[16:17], 0, v110, s[16:17]
	v_addc_co_u32_e64 v111, s[18:19], 0, v111, s[18:19]
	s_mov_b32 s10, 0xfcfcfcfc
	s_mov_b32 s11, s10
	s_mov_b32 s12, 0xfefefefe
	s_mov_b32 s13, s12
	v_cmp_gt_f32_e32 vcc, v80, v72
	v_cmp_ge_f32_e64 s[38:39], v80, v72
	v_cmp_gt_f32_e64 s[14:15], v80, v73
	v_cmp_ge_f32_e64 s[40:41], v80, v73
	v_cmp_gt_f32_e64 s[16:17], v80, v74
	v_cmp_ge_f32_e64 s[52:53], v80, v74
	v_cmp_gt_f32_e64 s[18:19], v80, v75
	v_cmp_ge_f32_e64 s[62:63], v80, v75
	s_and_b64 s[38:39], s[38:39], s[10:11]
	s_or_b64 vcc, vcc, s[38:39]
	s_and_b64 s[40:41], s[40:41], s[12:13]
	s_or_b64 s[14:15], s[14:15], s[40:41]
	s_and_b64 s[52:53], s[52:53], s[12:13]
	s_or_b64 s[16:17], s[16:17], s[52:53]
	s_and_b64 s[62:63], s[62:63], s[12:13]
	s_or_b64 s[18:19], s[18:19], s[62:63]
	v_addc_co_u32_e32 v108, vcc, 0, v108, vcc
	v_addc_co_u32_e64 v109, s[14:15], 0, v109, s[14:15]
	v_addc_co_u32_e64 v110, s[16:17], 0, v110, s[16:17]
	v_addc_co_u32_e64 v111, s[18:19], 0, v111, s[18:19]
	s_mov_b32 s10, 0xfcfcfcfc
	s_mov_b32 s11, s10
	s_mov_b32 s12, 0xfefefefe
	s_mov_b32 s13, s12
	v_cmp_gt_f32_e32 vcc, v81, v72
	v_cmp_ge_f32_e64 s[38:39], v81, v72
	v_cmp_gt_f32_e64 s[14:15], v81, v73
	v_cmp_ge_f32_e64 s[40:41], v81, v73
	v_cmp_gt_f32_e64 s[16:17], v81, v74
	v_cmp_ge_f32_e64 s[52:53], v81, v74
	v_cmp_gt_f32_e64 s[18:19], v81, v75
	v_cmp_ge_f32_e64 s[62:63], v81, v75
	s_and_b64 s[38:39], s[38:39], s[10:11]
	s_or_b64 vcc, vcc, s[38:39]
	s_and_b64 s[40:41], s[40:41], s[10:11]
	s_or_b64 s[14:15], s[14:15], s[40:41]
	s_and_b64 s[52:53], s[52:53], s[12:13]
	s_or_b64 s[16:17], s[16:17], s[52:53]
	s_and_b64 s[62:63], s[62:63], s[12:13]
	s_or_b64 s[18:19], s[18:19], s[62:63]
	v_addc_co_u32_e32 v108, vcc, 0, v108, vcc
	v_addc_co_u32_e64 v109, s[14:15], 0, v109, s[14:15]
	v_addc_co_u32_e64 v110, s[16:17], 0, v110, s[16:17]
	v_addc_co_u32_e64 v111, s[18:19], 0, v111, s[18:19]
	s_mov_b32 s10, 0xfcfcfcfc
	s_mov_b32 s11, s10
	s_mov_b32 s12, 0xfefefefe
	s_mov_b32 s13, s12
	v_cmp_gt_f32_e32 vcc, v82, v72
	v_cmp_ge_f32_e64 s[38:39], v82, v72
	v_cmp_gt_f32_e64 s[14:15], v82, v73
	v_cmp_ge_f32_e64 s[40:41], v82, v73
	v_cmp_gt_f32_e64 s[16:17], v82, v74
	v_cmp_ge_f32_e64 s[52:53], v82, v74
	v_cmp_gt_f32_e64 s[18:19], v82, v75
	v_cmp_ge_f32_e64 s[62:63], v82, v75
	s_and_b64 s[38:39], s[38:39], s[10:11]
	s_or_b64 vcc, vcc, s[38:39]
	s_and_b64 s[40:41], s[40:41], s[10:11]
	s_or_b64 s[14:15], s[14:15], s[40:41]
	s_and_b64 s[52:53], s[52:53], s[10:11]
	s_or_b64 s[16:17], s[16:17], s[52:53]
	s_and_b64 s[62:63], s[62:63], s[12:13]
	s_or_b64 s[18:19], s[18:19], s[62:63]
	v_addc_co_u32_e32 v108, vcc, 0, v108, vcc
	v_addc_co_u32_e64 v109, s[14:15], 0, v109, s[14:15]
	v_addc_co_u32_e64 v110, s[16:17], 0, v110, s[16:17]
	v_addc_co_u32_e64 v111, s[18:19], 0, v111, s[18:19]
	s_mov_b32 s10, 0xfcfcfcfc
	s_mov_b32 s11, s10
	v_cmp_gt_f32_e32 vcc, v83, v72
	v_cmp_ge_f32_e64 s[38:39], v83, v72
	v_cmp_gt_f32_e64 s[14:15], v83, v73
	v_cmp_ge_f32_e64 s[40:41], v83, v73
	v_cmp_gt_f32_e64 s[16:17], v83, v74
	v_cmp_ge_f32_e64 s[52:53], v83, v74
	v_cmp_gt_f32_e64 s[18:19], v83, v75
	v_cmp_ge_f32_e64 s[62:63], v83, v75
	s_and_b64 s[38:39], s[38:39], s[10:11]
	s_or_b64 vcc, vcc, s[38:39]
	s_and_b64 s[40:41], s[40:41], s[10:11]
	s_or_b64 s[14:15], s[14:15], s[40:41]
	s_and_b64 s[52:53], s[52:53], s[10:11]
	s_or_b64 s[16:17], s[16:17], s[52:53]
	s_and_b64 s[62:63], s[62:63], s[10:11]
	s_or_b64 s[18:19], s[18:19], s[62:63]
	v_addc_co_u32_e32 v108, vcc, 0, v108, vcc
	v_addc_co_u32_e64 v109, s[14:15], 0, v109, s[14:15]
	v_addc_co_u32_e64 v110, s[16:17], 0, v110, s[16:17]
	v_addc_co_u32_e64 v111, s[18:19], 0, v111, s[18:19]
	s_mov_b32 s10, 0xf8f8f8f8
	s_mov_b32 s11, s10
	s_mov_b32 s12, 0xfcfcfcfc
	s_mov_b32 s13, s12
	v_cmp_gt_f32_e32 vcc, v84, v72
	v_cmp_ge_f32_e64 s[38:39], v84, v72
	v_cmp_gt_f32_e64 s[14:15], v84, v73
	v_cmp_ge_f32_e64 s[40:41], v84, v73
	v_cmp_gt_f32_e64 s[16:17], v84, v74
	v_cmp_ge_f32_e64 s[52:53], v84, v74
	v_cmp_gt_f32_e64 s[18:19], v84, v75
	v_cmp_ge_f32_e64 s[62:63], v84, v75
	s_and_b64 s[38:39], s[38:39], s[10:11]
	s_or_b64 vcc, vcc, s[38:39]
	s_and_b64 s[40:41], s[40:41], s[12:13]
	s_or_b64 s[14:15], s[14:15], s[40:41]
	s_and_b64 s[52:53], s[52:53], s[12:13]
	s_or_b64 s[16:17], s[16:17], s[52:53]
	s_and_b64 s[62:63], s[62:63], s[12:13]
	s_or_b64 s[18:19], s[18:19], s[62:63]
	v_addc_co_u32_e32 v108, vcc, 0, v108, vcc
	v_addc_co_u32_e64 v109, s[14:15], 0, v109, s[14:15]
	v_addc_co_u32_e64 v110, s[16:17], 0, v110, s[16:17]
	v_addc_co_u32_e64 v111, s[18:19], 0, v111, s[18:19]
	s_mov_b32 s10, 0xf8f8f8f8
	s_mov_b32 s11, s10
	s_mov_b32 s12, 0xfcfcfcfc
	s_mov_b32 s13, s12
	v_cmp_gt_f32_e32 vcc, v85, v72
	v_cmp_ge_f32_e64 s[38:39], v85, v72
	v_cmp_gt_f32_e64 s[14:15], v85, v73
	v_cmp_ge_f32_e64 s[40:41], v85, v73
	v_cmp_gt_f32_e64 s[16:17], v85, v74
	v_cmp_ge_f32_e64 s[52:53], v85, v74
	v_cmp_gt_f32_e64 s[18:19], v85, v75
	v_cmp_ge_f32_e64 s[62:63], v85, v75
	s_and_b64 s[38:39], s[38:39], s[10:11]
	s_or_b64 vcc, vcc, s[38:39]
	s_and_b64 s[40:41], s[40:41], s[10:11]
	s_or_b64 s[14:15], s[14:15], s[40:41]
	s_and_b64 s[52:53], s[52:53], s[12:13]
	s_or_b64 s[16:17], s[16:17], s[52:53]
	s_and_b64 s[62:63], s[62:63], s[12:13]
	s_or_b64 s[18:19], s[18:19], s[62:63]
	v_addc_co_u32_e32 v108, vcc, 0, v108, vcc
	v_addc_co_u32_e64 v109, s[14:15], 0, v109, s[14:15]
	v_addc_co_u32_e64 v110, s[16:17], 0, v110, s[16:17]
	v_addc_co_u32_e64 v111, s[18:19], 0, v111, s[18:19]
	s_mov_b32 s10, 0xf8f8f8f8
	s_mov_b32 s11, s10
; __device__ __forceinline__ void nsa_mfma_phase(const bf16* z, const bf16* kch, const bf16* kcl, const bf16* vct, const bf16* vst, const bf16* vwt, const float* biasTab, bf16* oc,
;                                                LAS unsigned char* lds, int tid0, int vcu, int G) {
;     ...
;                   for (int jj = 0; jj < 4; ++jj) { const int j = jg * 4 + jj; if (j < 1 || j > qb - 2) continue;
;                       const float x = (i0[j] * w0 + i0[64 * 33 + j] * w1) + (i0[2 * 64 * 33 + j] * w2 + i0[3 * 64 * 33 + j] * w3); int cnt = 0;
;                       for (int j2 = 1; j2 <= qb - 2; ++j2) { const float y = (i0[j2] * w0 + i0[64 * 33 + j2] * w1) + (i0[2 * 64 * 33 + j2] * w2 + i0[3 * 64 * 33 + j2] * w3); cnt += (y > x || (y == x && j2 < j)) ? 1 : 0; }
	s_mov_b32 s12, 0xfcfcfcfc
	s_mov_b32 s13, s12
	v_cmp_gt_f32_e32 vcc, v86, v72
	v_cmp_ge_f32_e64 s[38:39], v86, v72
	v_cmp_gt_f32_e64 s[14:15], v86, v73
	v_cmp_ge_f32_e64 s[40:41], v86, v73
	v_cmp_gt_f32_e64 s[16:17], v86, v74
	v_cmp_ge_f32_e64 s[52:53], v86, v74
	v_cmp_gt_f32_e64 s[18:19], v86, v75
	v_cmp_ge_f32_e64 s[62:63], v86, v75
	s_and_b64 s[38:39], s[38:39], s[10:11]
	s_or_b64 vcc, vcc, s[38:39]
	s_and_b64 s[40:41], s[40:41], s[10:11]
	s_or_b64 s[14:15], s[14:15], s[40:41]
	s_and_b64 s[52:53], s[52:53], s[10:11]
	s_or_b64 s[16:17], s[16:17], s[52:53]
	s_and_b64 s[62:63], s[62:63], s[12:13]
	s_or_b64 s[18:19], s[18:19], s[62:63]
	v_addc_co_u32_e32 v108, vcc, 0, v108, vcc
	v_addc_co_u32_e64 v109, s[14:15], 0, v109, s[14:15]
	v_addc_co_u32_e64 v110, s[16:17], 0, v110, s[16:17]
	v_addc_co_u32_e64 v111, s[18:19], 0, v111, s[18:19]
	s_mov_b32 s10, 0xf8f8f8f8
	s_mov_b32 s11, s10
	v_cmp_gt_f32_e32 vcc, v87, v72
	v_cmp_ge_f32_e64 s[38:39], v87, v72
	v_cmp_gt_f32_e64 s[14:15], v87, v73
	v_cmp_ge_f32_e64 s[40:41], v87, v73
	v_cmp_gt_f32_e64 s[16:17], v87, v74
	v_cmp_ge_f32_e64 s[52:53], v87, v74
	v_cmp_gt_f32_e64 s[18:19], v87, v75
	v_cmp_ge_f32_e64 s[62:63], v87, v75
	s_and_b64 s[38:39], s[38:39], s[10:11]
	s_or_b64 vcc, vcc, s[38:39]
	s_and_b64 s[40:41], s[40:41], s[10:11]
	s_or_b64 s[14:15], s[14:15], s[40:41]
	s_and_b64 s[52:53], s[52:53], s[10:11]
	s_or_b64 s[16:17], s[16:17], s[52:53]
	s_and_b64 s[62:63], s[62:63], s[10:11]
	s_or_b64 s[18:19], s[18:19], s[62:63]
	v_addc_co_u32_e32 v108, vcc, 0, v108, vcc
	v_addc_co_u32_e64 v109, s[14:15], 0, v109, s[14:15]
	v_addc_co_u32_e64 v110, s[16:17], 0, v110, s[16:17]
	v_addc_co_u32_e64 v111, s[18:19], 0, v111, s[18:19]
	s_mov_b32 s10, 0xf0f0f0f0
	s_mov_b32 s11, s10
	s_mov_b32 s12, 0xf8f8f8f8
	s_mov_b32 s13, s12
	v_cmp_gt_f32_e32 vcc, v88, v72
	v_cmp_ge_f32_e64 s[38:39], v88, v72
	v_cmp_gt_f32_e64 s[14:15], v88, v73
	v_cmp_ge_f32_e64 s[40:41], v88, v73
	v_cmp_gt_f32_e64 s[16:17], v88, v74
	v_cmp_ge_f32_e64 s[52:53], v88, v74
	v_cmp_gt_f32_e64 s[18:19], v88, v75
	v_cmp_ge_f32_e64 s[62:63], v88, v75
	s_and_b64 s[38:39], s[38:39], s[10:11]
	s_or_b64 vcc, vcc, s[38:39]
	s_and_b64 s[40:41], s[40:41], s[12:13]
	s_or_b64 s[14:15], s[14:15], s[40:41]
	s_and_b64 s[52:53], s[52:53], s[12:13]
	s_or_b64 s[16:17], s[16:17], s[52:53]
	s_and_b64 s[62:63], s[62:63], s[12:13]
	s_or_b64 s[18:19], s[18:19], s[62:63]
	v_addc_co_u32_e32 v108, vcc, 0, v108, vcc
	v_addc_co_u32_e64 v109, s[14:15], 0, v109, s[14:15]
	v_addc_co_u32_e64 v110, s[16:17], 0, v110, s[16:17]
	v_addc_co_u32_e64 v111, s[18:19], 0, v111, s[18:19]
	s_mov_b32 s10, 0xf0f0f0f0
	s_mov_b32 s11, s10
	s_mov_b32 s12, 0xf8f8f8f8
	s_mov_b32 s13, s12
	v_cmp_gt_f32_e32 vcc, v89, v72
	v_cmp_ge_f32_e64 s[38:39], v89, v72
	v_cmp_gt_f32_e64 s[14:15], v89, v73
	v_cmp_ge_f32_e64 s[40:41], v89, v73
	v_cmp_gt_f32_e64 s[16:17], v89, v74
	v_cmp_ge_f32_e64 s[52:53], v89, v74
	v_cmp_gt_f32_e64 s[18:19], v89, v75
	v_cmp_ge_f32_e64 s[62:63], v89, v75
	s_and_b64 s[38:39], s[38:39], s[10:11]
	s_or_b64 vcc, vcc, s[38:39]
	s_and_b64 s[40:41], s[40:41], s[10:11]
	s_or_b64 s[14:15], s[14:15], s[40:41]
	s_and_b64 s[52:53], s[52:53], s[12:13]
	s_or_b64 s[16:17], s[16:17], s[52:53]
	s_and_b64 s[62:63], s[62:63], s[12:13]
	s_or_b64 s[18:19], s[18:19], s[62:63]
	v_addc_co_u32_e32 v108, vcc, 0, v108, vcc
	v_addc_co_u32_e64 v109, s[14:15], 0, v109, s[14:15]
	v_addc_co_u32_e64 v110, s[16:17], 0, v110, s[16:17]
	v_addc_co_u32_e64 v111, s[18:19], 0, v111, s[18:19]
	s_mov_b32 s10, 0xf0f0f0f0
	s_mov_b32 s11, s10
	s_mov_b32 s12, 0xf8f8f8f8
	s_mov_b32 s13, s12
	v_cmp_gt_f32_e32 vcc, v90, v72
	v_cmp_ge_f32_e64 s[38:39], v90, v72
	v_cmp_gt_f32_e64 s[14:15], v90, v73
	v_cmp_ge_f32_e64 s[40:41], v90, v73
	v_cmp_gt_f32_e64 s[16:17], v90, v74
	v_cmp_ge_f32_e64 s[52:53], v90, v74
	v_cmp_gt_f32_e64 s[18:19], v90, v75
	v_cmp_ge_f32_e64 s[62:63], v90, v75
	s_and_b64 s[38:39], s[38:39], s[10:11]
	s_or_b64 vcc, vcc, s[38:39]
	s_and_b64 s[40:41], s[40:41], s[10:11]
	s_or_b64 s[14:15], s[14:15], s[40:41]
	s_and_b64 s[52:53], s[52:53], s[10:11]
	s_or_b64 s[16:17], s[16:17], s[52:53]
	s_and_b64 s[62:63], s[62:63], s[12:13]
	s_or_b64 s[18:19], s[18:19], s[62:63]
	v_addc_co_u32_e32 v108, vcc, 0, v108, vcc
	v_addc_co_u32_e64 v109, s[14:15], 0, v109, s[14:15]
	v_addc_co_u32_e64 v110, s[16:17], 0, v110, s[16:17]
	v_addc_co_u32_e64 v111, s[18:19], 0, v111, s[18:19]
	s_cmp_eq_u32 s37, 14
	s_cbranch_scc1 .Ltk_done
	s_mov_b32 s10, 0xf0f0f0f0
	s_mov_b32 s11, s10
	v_cmp_gt_f32_e32 vcc, v91, v72
	v_cmp_ge_f32_e64 s[38:39], v91, v72
	v_cmp_gt_f32_e64 s[14:15], v91, v73
	v_cmp_ge_f32_e64 s[40:41], v91, v73
	v_cmp_gt_f32_e64 s[16:17], v91, v74
	v_cmp_ge_f32_e64 s[52:53], v91, v74
	v_cmp_gt_f32_e64 s[18:19], v91, v75
	v_cmp_ge_f32_e64 s[62:63], v91, v75
	s_and_b64 s[38:39], s[38:39], s[10:11]
	s_or_b64 vcc, vcc, s[38:39]
	s_and_b64 s[40:41], s[40:41], s[10:11]
	s_or_b64 s[14:15], s[14:15], s[40:41]
	s_and_b64 s[52:53], s[52:53], s[10:11]
	s_or_b64 s[16:17], s[16:17], s[52:53]
	s_and_b64 s[62:63], s[62:63], s[10:11]
	s_or_b64 s[18:19], s[18:19], s[62:63]
	v_addc_co_u32_e32 v108, vcc, 0, v108, vcc
	v_addc_co_u32_e64 v109, s[14:15], 0, v109, s[14:15]
	v_addc_co_u32_e64 v110, s[16:17], 0, v110, s[16:17]
	v_addc_co_u32_e64 v111, s[18:19], 0, v111, s[18:19]
	s_cmp_eq_u32 s37, 15
	s_cbranch_scc1 .Ltk_done
; __device__ __forceinline__ void nsa_mfma_phase(const bf16* z, const bf16* kch, const bf16* kcl, const bf16* vct, const bf16* vst, const bf16* vwt, const float* biasTab, bf16* oc,
;                                                LAS unsigned char* lds, int tid0, int vcu, int G) {
;     ...
;                   for (int jj = 0; jj < 4; ++jj) { const int j = jg * 4 + jj; if (j < 1 || j > qb - 2) continue;
;                       const float x = (i0[j] * w0 + i0[64 * 33 + j] * w1) + (i0[2 * 64 * 33 + j] * w2 + i0[3 * 64 * 33 + j] * w3); int cnt = 0;
;                       for (int j2 = 1; j2 <= qb - 2; ++j2) { const float y = (i0[j2] * w0 + i0[64 * 33 + j2] * w1) + (i0[2 * 64 * 33 + j2] * w2 + i0[3 * 64 * 33 + j2] * w3); cnt += (y > x || (y == x && j2 < j)) ? 1 : 0; }
	s_mov_b32 s10, 0xe0e0e0e0
	s_mov_b32 s11, s10
	s_mov_b32 s12, 0xf0f0f0f0
	s_mov_b32 s13, s12
	v_cmp_gt_f32_e32 vcc, v92, v72
	v_cmp_ge_f32_e64 s[38:39], v92, v72
	v_cmp_gt_f32_e64 s[14:15], v92, v73
	v_cmp_ge_f32_e64 s[40:41], v92, v73
	v_cmp_gt_f32_e64 s[16:17], v92, v74
	v_cmp_ge_f32_e64 s[52:53], v92, v74
	v_cmp_gt_f32_e64 s[18:19], v92, v75
	v_cmp_ge_f32_e64 s[62:63], v92, v75
	s_and_b64 s[38:39], s[38:39], s[10:11]
	s_or_b64 vcc, vcc, s[38:39]
	s_and_b64 s[40:41], s[40:41], s[12:13]
	s_or_b64 s[14:15], s[14:15], s[40:41]
	s_and_b64 s[52:53], s[52:53], s[12:13]
	s_or_b64 s[16:17], s[16:17], s[52:53]
	s_and_b64 s[62:63], s[62:63], s[12:13]
	s_or_b64 s[18:19], s[18:19], s[62:63]
	v_addc_co_u32_e32 v108, vcc, 0, v108, vcc
	v_addc_co_u32_e64 v109, s[14:15], 0, v109, s[14:15]
	v_addc_co_u32_e64 v110, s[16:17], 0, v110, s[16:17]
	v_addc_co_u32_e64 v111, s[18:19], 0, v111, s[18:19]
	s_cmp_eq_u32 s37, 16
	s_cbranch_scc1 .Ltk_done
	s_mov_b32 s10, 0xe0e0e0e0
	s_mov_b32 s11, s10
	s_mov_b32 s12, 0xf0f0f0f0
	s_mov_b32 s13, s12
	v_cmp_gt_f32_e32 vcc, v93, v72
	v_cmp_ge_f32_e64 s[38:39], v93, v72
	v_cmp_gt_f32_e64 s[14:15], v93, v73
	v_cmp_ge_f32_e64 s[40:41], v93, v73
	v_cmp_gt_f32_e64 s[16:17], v93, v74
	v_cmp_ge_f32_e64 s[52:53], v93, v74
	v_cmp_gt_f32_e64 s[18:19], v93, v75
	v_cmp_ge_f32_e64 s[62:63], v93, v75
	s_and_b64 s[38:39], s[38:39], s[10:11]
	s_or_b64 vcc, vcc, s[38:39]
	s_and_b64 s[40:41], s[40:41], s[10:11]
	s_or_b64 s[14:15], s[14:15], s[40:41]
	s_and_b64 s[52:53], s[52:53], s[12:13]
	s_or_b64 s[16:17], s[16:17], s[52:53]
	s_and_b64 s[62:63], s[62:63], s[12:13]
	s_or_b64 s[18:19], s[18:19], s[62:63]
	v_addc_co_u32_e32 v108, vcc, 0, v108, vcc
	v_addc_co_u32_e64 v109, s[14:15], 0, v109, s[14:15]
	v_addc_co_u32_e64 v110, s[16:17], 0, v110, s[16:17]
	v_addc_co_u32_e64 v111, s[18:19], 0, v111, s[18:19]
	s_cmp_eq_u32 s37, 17
	s_cbranch_scc1 .Ltk_done
	s_mov_b32 s10, 0xe0e0e0e0
	s_mov_b32 s11, s10
	s_mov_b32 s12, 0xf0f0f0f0
	s_mov_b32 s13, s12
	v_cmp_gt_f32_e32 vcc, v94, v72
	v_cmp_ge_f32_e64 s[38:39], v94, v72
	v_cmp_gt_f32_e64 s[14:15], v94, v73
	v_cmp_ge_f32_e64 s[40:41], v94, v73
	v_cmp_gt_f32_e64 s[16:17], v94, v74
	v_cmp_ge_f32_e64 s[52:53], v94, v74
	v_cmp_gt_f32_e64 s[18:19], v94, v75
	v_cmp_ge_f32_e64 s[62:63], v94, v75
	s_and_b64 s[38:39], s[38:39], s[10:11]
	s_or_b64 vcc, vcc, s[38:39]
	s_and_b64 s[40:41], s[40:41], s[10:11]
	s_or_b64 s[14:15], s[14:15], s[40:41]
	s_and_b64 s[52:53], s[52:53], s[10:11]
	s_or_b64 s[16:17], s[16:17], s[52:53]
	s_and_b64 s[62:63], s[62:63], s[12:13]
	s_or_b64 s[18:19], s[18:19], s[62:63]
	v_addc_co_u32_e32 v108, vcc, 0, v108, vcc
	v_addc_co_u32_e64 v109, s[14:15], 0, v109, s[14:15]
	v_addc_co_u32_e64 v110, s[16:17], 0, v110, s[16:17]
	v_addc_co_u32_e64 v111, s[18:19], 0, v111, s[18:19]
	s_cmp_eq_u32 s37, 18
	s_cbranch_scc1 .Ltk_done
	s_mov_b32 s10, 0xe0e0e0e0
	s_mov_b32 s11, s10
	v_cmp_gt_f32_e32 vcc, v95, v72
	v_cmp_ge_f32_e64 s[38:39], v95, v72
	v_cmp_gt_f32_e64 s[14:15], v95, v73
	v_cmp_ge_f32_e64 s[40:41], v95, v73
	v_cmp_gt_f32_e64 s[16:17], v95, v74
	v_cmp_ge_f32_e64 s[52:53], v95, v74
	v_cmp_gt_f32_e64 s[18:19], v95, v75
	v_cmp_ge_f32_e64 s[62:63], v95, v75
	s_and_b64 s[38:39], s[38:39], s[10:11]
	s_or_b64 vcc, vcc, s[38:39]
	s_and_b64 s[40:41], s[40:41], s[10:11]
	s_or_b64 s[14:15], s[14:15], s[40:41]
	s_and_b64 s[52:53], s[52:53], s[10:11]
	s_or_b64 s[16:17], s[16:17], s[52:53]
	s_and_b64 s[62:63], s[62:63], s[10:11]
	s_or_b64 s[18:19], s[18:19], s[62:63]
	v_addc_co_u32_e32 v108, vcc, 0, v108, vcc
	v_addc_co_u32_e64 v109, s[14:15], 0, v109, s[14:15]
	v_addc_co_u32_e64 v110, s[16:17], 0, v110, s[16:17]
	v_addc_co_u32_e64 v111, s[18:19], 0, v111, s[18:19]
	s_cmp_eq_u32 s37, 19
	s_cbranch_scc1 .Ltk_done
	s_mov_b32 s10, 0xc0c0c0c0
	s_mov_b32 s11, s10
	s_mov_b32 s12, 0xe0e0e0e0
	s_mov_b32 s13, s12
	v_cmp_gt_f32_e32 vcc, v96, v72
	v_cmp_ge_f32_e64 s[38:39], v96, v72
	v_cmp_gt_f32_e64 s[14:15], v96, v73
	v_cmp_ge_f32_e64 s[40:41], v96, v73
	v_cmp_gt_f32_e64 s[16:17], v96, v74
	v_cmp_ge_f32_e64 s[52:53], v96, v74
	v_cmp_gt_f32_e64 s[18:19], v96, v75
	v_cmp_ge_f32_e64 s[62:63], v96, v75
	s_and_b64 s[38:39], s[38:39], s[10:11]
	s_or_b64 vcc, vcc, s[38:39]
	s_and_b64 s[40:41], s[40:41], s[12:13]
	s_or_b64 s[14:15], s[14:15], s[40:41]
	s_and_b64 s[52:53], s[52:53], s[12:13]
	s_or_b64 s[16:17], s[16:17], s[52:53]
	s_and_b64 s[62:63], s[62:63], s[12:13]
	s_or_b64 s[18:19], s[18:19], s[62:63]
	v_addc_co_u32_e32 v108, vcc, 0, v108, vcc
	v_addc_co_u32_e64 v109, s[14:15], 0, v109, s[14:15]
	v_addc_co_u32_e64 v110, s[16:17], 0, v110, s[16:17]
	v_addc_co_u32_e64 v111, s[18:19], 0, v111, s[18:19]
	s_cmp_eq_u32 s37, 20
	s_cbranch_scc1 .Ltk_done
	s_mov_b32 s10, 0xc0c0c0c0
	s_mov_b32 s11, s10
	s_mov_b32 s12, 0xe0e0e0e0
	s_mov_b32 s13, s12
	v_cmp_gt_f32_e32 vcc, v97, v72
	v_cmp_ge_f32_e64 s[38:39], v97, v72
	v_cmp_gt_f32_e64 s[14:15], v97, v73
	v_cmp_ge_f32_e64 s[40:41], v97, v73
	v_cmp_gt_f32_e64 s[16:17], v97, v74
	v_cmp_ge_f32_e64 s[52:53], v97, v74
	v_cmp_gt_f32_e64 s[18:19], v97, v75
	v_cmp_ge_f32_e64 s[62:63], v97, v75
	s_and_b64 s[38:39], s[38:39], s[10:11]
	s_or_b64 vcc, vcc, s[38:39]
	s_and_b64 s[40:41], s[40:41], s[10:11]
	s_or_b64 s[14:15], s[14:15], s[40:41]
	s_and_b64 s[52:53], s[52:53], s[12:13]
	s_or_b64 s[16:17], s[16:17], s[52:53]
	s_and_b64 s[62:63], s[62:63], s[12:13]
	s_or_b64 s[18:19], s[18:19], s[62:63]
	v_addc_co_u32_e32 v108, vcc, 0, v108, vcc
	v_addc_co_u32_e64 v109, s[14:15], 0, v109, s[14:15]
	v_addc_co_u32_e64 v110, s[16:17], 0, v110, s[16:17]
	v_addc_co_u32_e64 v111, s[18:19], 0, v111, s[18:19]
	s_cmp_eq_u32 s37, 21
	s_cbranch_scc1 .Ltk_done
; __device__ __forceinline__ void nsa_mfma_phase(const bf16* z, const bf16* kch, const bf16* kcl, const bf16* vct, const bf16* vst, const bf16* vwt, const float* biasTab, bf16* oc,
;                                                LAS unsigned char* lds, int tid0, int vcu, int G) {
;     ...
;                   for (int jj = 0; jj < 4; ++jj) { const int j = jg * 4 + jj; if (j < 1 || j > qb - 2) continue;
;                       const float x = (i0[j] * w0 + i0[64 * 33 + j] * w1) + (i0[2 * 64 * 33 + j] * w2 + i0[3 * 64 * 33 + j] * w3); int cnt = 0;
;                       for (int j2 = 1; j2 <= qb - 2; ++j2) { const float y = (i0[j2] * w0 + i0[64 * 33 + j2] * w1) + (i0[2 * 64 * 33 + j2] * w2 + i0[3 * 64 * 33 + j2] * w3); cnt += (y > x || (y == x && j2 < j)) ? 1 : 0; }
	s_mov_b32 s10, 0xc0c0c0c0
	s_mov_b32 s11, s10
	s_mov_b32 s12, 0xe0e0e0e0
	s_mov_b32 s13, s12
	v_cmp_gt_f32_e32 vcc, v98, v72
	v_cmp_ge_f32_e64 s[38:39], v98, v72
	v_cmp_gt_f32_e64 s[14:15], v98, v73
	v_cmp_ge_f32_e64 s[40:41], v98, v73
	v_cmp_gt_f32_e64 s[16:17], v98, v74
	v_cmp_ge_f32_e64 s[52:53], v98, v74
	v_cmp_gt_f32_e64 s[18:19], v98, v75
	v_cmp_ge_f32_e64 s[62:63], v98, v75
	s_and_b64 s[38:39], s[38:39], s[10:11]
	s_or_b64 vcc, vcc, s[38:39]
	s_and_b64 s[40:41], s[40:41], s[10:11]
	s_or_b64 s[14:15], s[14:15], s[40:41]
	s_and_b64 s[52:53], s[52:53], s[10:11]
	s_or_b64 s[16:17], s[16:17], s[52:53]
	s_and_b64 s[62:63], s[62:63], s[12:13]
	s_or_b64 s[18:19], s[18:19], s[62:63]
	v_addc_co_u32_e32 v108, vcc, 0, v108, vcc
	v_addc_co_u32_e64 v109, s[14:15], 0, v109, s[14:15]
	v_addc_co_u32_e64 v110, s[16:17], 0, v110, s[16:17]
	v_addc_co_u32_e64 v111, s[18:19], 0, v111, s[18:19]
	s_cmp_eq_u32 s37, 22
	s_cbranch_scc1 .Ltk_done
	s_mov_b32 s10, 0xc0c0c0c0
	s_mov_b32 s11, s10
	v_cmp_gt_f32_e32 vcc, v99, v72
	v_cmp_ge_f32_e64 s[38:39], v99, v72
	v_cmp_gt_f32_e64 s[14:15], v99, v73
	v_cmp_ge_f32_e64 s[40:41], v99, v73
	v_cmp_gt_f32_e64 s[16:17], v99, v74
	v_cmp_ge_f32_e64 s[52:53], v99, v74
	v_cmp_gt_f32_e64 s[18:19], v99, v75
	v_cmp_ge_f32_e64 s[62:63], v99, v75
	s_and_b64 s[38:39], s[38:39], s[10:11]
	s_or_b64 vcc, vcc, s[38:39]
	s_and_b64 s[40:41], s[40:41], s[10:11]
	s_or_b64 s[14:15], s[14:15], s[40:41]
	s_and_b64 s[52:53], s[52:53], s[10:11]
	s_or_b64 s[16:17], s[16:17], s[52:53]
	s_and_b64 s[62:63], s[62:63], s[10:11]
	s_or_b64 s[18:19], s[18:19], s[62:63]
	v_addc_co_u32_e32 v108, vcc, 0, v108, vcc
	v_addc_co_u32_e64 v109, s[14:15], 0, v109, s[14:15]
	v_addc_co_u32_e64 v110, s[16:17], 0, v110, s[16:17]
	v_addc_co_u32_e64 v111, s[18:19], 0, v111, s[18:19]
	s_cmp_eq_u32 s37, 23
	s_cbranch_scc1 .Ltk_done
	s_mov_b32 s10, 0x80808080
	s_mov_b32 s11, s10
	s_mov_b32 s12, 0xc0c0c0c0
	s_mov_b32 s13, s12
	v_cmp_gt_f32_e32 vcc, v100, v72
	v_cmp_ge_f32_e64 s[38:39], v100, v72
	v_cmp_gt_f32_e64 s[14:15], v100, v73
	v_cmp_ge_f32_e64 s[40:41], v100, v73
	v_cmp_gt_f32_e64 s[16:17], v100, v74
	v_cmp_ge_f32_e64 s[52:53], v100, v74
	v_cmp_gt_f32_e64 s[18:19], v100, v75
	v_cmp_ge_f32_e64 s[62:63], v100, v75
	s_and_b64 s[38:39], s[38:39], s[10:11]
	s_or_b64 vcc, vcc, s[38:39]
	s_and_b64 s[40:41], s[40:41], s[12:13]
	s_or_b64 s[14:15], s[14:15], s[40:41]
	s_and_b64 s[52:53], s[52:53], s[12:13]
	s_or_b64 s[16:17], s[16:17], s[52:53]
	s_and_b64 s[62:63], s[62:63], s[12:13]
	s_or_b64 s[18:19], s[18:19], s[62:63]
	v_addc_co_u32_e32 v108, vcc, 0, v108, vcc
	v_addc_co_u32_e64 v109, s[14:15], 0, v109, s[14:15]
	v_addc_co_u32_e64 v110, s[16:17], 0, v110, s[16:17]
	v_addc_co_u32_e64 v111, s[18:19], 0, v111, s[18:19]
	s_cmp_eq_u32 s37, 24
	s_cbranch_scc1 .Ltk_done
	s_mov_b32 s10, 0x80808080
	s_mov_b32 s11, s10
	s_mov_b32 s12, 0xc0c0c0c0
	s_mov_b32 s13, s12
	v_cmp_gt_f32_e32 vcc, v101, v72
	v_cmp_ge_f32_e64 s[38:39], v101, v72
	v_cmp_gt_f32_e64 s[14:15], v101, v73
	v_cmp_ge_f32_e64 s[40:41], v101, v73
	v_cmp_gt_f32_e64 s[16:17], v101, v74
	v_cmp_ge_f32_e64 s[52:53], v101, v74
	v_cmp_gt_f32_e64 s[18:19], v101, v75
	v_cmp_ge_f32_e64 s[62:63], v101, v75
	s_and_b64 s[38:39], s[38:39], s[10:11]
	s_or_b64 vcc, vcc, s[38:39]
	s_and_b64 s[40:41], s[40:41], s[10:11]
	s_or_b64 s[14:15], s[14:15], s[40:41]
	s_and_b64 s[52:53], s[52:53], s[12:13]
	s_or_b64 s[16:17], s[16:17], s[52:53]
	s_and_b64 s[62:63], s[62:63], s[12:13]
	s_or_b64 s[18:19], s[18:19], s[62:63]
	v_addc_co_u32_e32 v108, vcc, 0, v108, vcc
	v_addc_co_u32_e64 v109, s[14:15], 0, v109, s[14:15]
	v_addc_co_u32_e64 v110, s[16:17], 0, v110, s[16:17]
	v_addc_co_u32_e64 v111, s[18:19], 0, v111, s[18:19]
	s_cmp_eq_u32 s37, 25
	s_cbranch_scc1 .Ltk_done
	s_mov_b32 s10, 0x80808080
	s_mov_b32 s11, s10
	s_mov_b32 s12, 0xc0c0c0c0
	s_mov_b32 s13, s12
	v_cmp_gt_f32_e32 vcc, v102, v72
	v_cmp_ge_f32_e64 s[38:39], v102, v72
	v_cmp_gt_f32_e64 s[14:15], v102, v73
	v_cmp_ge_f32_e64 s[40:41], v102, v73
	v_cmp_gt_f32_e64 s[16:17], v102, v74
	v_cmp_ge_f32_e64 s[52:53], v102, v74
	v_cmp_gt_f32_e64 s[18:19], v102, v75
	v_cmp_ge_f32_e64 s[62:63], v102, v75
	s_and_b64 s[38:39], s[38:39], s[10:11]
	s_or_b64 vcc, vcc, s[38:39]
	s_and_b64 s[40:41], s[40:41], s[10:11]
	s_or_b64 s[14:15], s[14:15], s[40:41]
	s_and_b64 s[52:53], s[52:53], s[10:11]
	s_or_b64 s[16:17], s[16:17], s[52:53]
	s_and_b64 s[62:63], s[62:63], s[12:13]
	s_or_b64 s[18:19], s[18:19], s[62:63]
	v_addc_co_u32_e32 v108, vcc, 0, v108, vcc
	v_addc_co_u32_e64 v109, s[14:15], 0, v109, s[14:15]
	v_addc_co_u32_e64 v110, s[16:17], 0, v110, s[16:17]
	v_addc_co_u32_e64 v111, s[18:19], 0, v111, s[18:19]
	s_cmp_eq_u32 s37, 26
	s_cbranch_scc1 .Ltk_done
	s_mov_b32 s10, 0x80808080
	s_mov_b32 s11, s10
	v_cmp_gt_f32_e32 vcc, v103, v72
	v_cmp_ge_f32_e64 s[38:39], v103, v72
	v_cmp_gt_f32_e64 s[14:15], v103, v73
	v_cmp_ge_f32_e64 s[40:41], v103, v73
	v_cmp_gt_f32_e64 s[16:17], v103, v74
	v_cmp_ge_f32_e64 s[52:53], v103, v74
	v_cmp_gt_f32_e64 s[18:19], v103, v75
	v_cmp_ge_f32_e64 s[62:63], v103, v75
	s_and_b64 s[38:39], s[38:39], s[10:11]
	s_or_b64 vcc, vcc, s[38:39]
	s_and_b64 s[40:41], s[40:41], s[10:11]
	s_or_b64 s[14:15], s[14:15], s[40:41]
	s_and_b64 s[52:53], s[52:53], s[10:11]
	s_or_b64 s[16:17], s[16:17], s[52:53]
	s_and_b64 s[62:63], s[62:63], s[10:11]
	s_or_b64 s[18:19], s[18:19], s[62:63]
	v_addc_co_u32_e32 v108, vcc, 0, v108, vcc
	v_addc_co_u32_e64 v109, s[14:15], 0, v109, s[14:15]
	v_addc_co_u32_e64 v110, s[16:17], 0, v110, s[16:17]
	v_addc_co_u32_e64 v111, s[18:19], 0, v111, s[18:19]
	s_cmp_eq_u32 s37, 27
	s_cbranch_scc1 .Ltk_done
	s_mov_b32 s10, 0x80808080
	s_mov_b32 s11, s10
	v_cmp_gt_f32_e32 vcc, v104, v72
	v_cmp_gt_f32_e64 s[14:15], v104, v73
	v_cmp_ge_f32_e64 s[40:41], v104, v73
	v_cmp_gt_f32_e64 s[16:17], v104, v74
	v_cmp_ge_f32_e64 s[52:53], v104, v74
	v_cmp_gt_f32_e64 s[18:19], v104, v75
	v_cmp_ge_f32_e64 s[62:63], v104, v75
	s_and_b64 s[40:41], s[40:41], s[10:11]
	s_or_b64 s[14:15], s[14:15], s[40:41]
	s_and_b64 s[52:53], s[52:53], s[10:11]
	s_or_b64 s[16:17], s[16:17], s[52:53]
	s_and_b64 s[62:63], s[62:63], s[10:11]
	s_or_b64 s[18:19], s[18:19], s[62:63]
	v_addc_co_u32_e32 v108, vcc, 0, v108, vcc
	v_addc_co_u32_e64 v109, s[14:15], 0, v109, s[14:15]
	v_addc_co_u32_e64 v110, s[16:17], 0, v110, s[16:17]
	v_addc_co_u32_e64 v111, s[18:19], 0, v111, s[18:19]
	s_cmp_eq_u32 s37, 28
	s_cbranch_scc1 .Ltk_done
	s_mov_b32 s10, 0x80808080
	s_mov_b32 s11, s10
	v_cmp_gt_f32_e32 vcc, v105, v72
	v_cmp_gt_f32_e64 s[14:15], v105, v73
	v_cmp_gt_f32_e64 s[16:17], v105, v74
	v_cmp_ge_f32_e64 s[52:53], v105, v74
	v_cmp_gt_f32_e64 s[18:19], v105, v75
	v_cmp_ge_f32_e64 s[62:63], v105, v75
	s_and_b64 s[52:53], s[52:53], s[10:11]
	s_or_b64 s[16:17], s[16:17], s[52:53]
	s_and_b64 s[62:63], s[62:63], s[10:11]
	s_or_b64 s[18:19], s[18:19], s[62:63]
	v_addc_co_u32_e32 v108, vcc, 0, v108, vcc
	v_addc_co_u32_e64 v109, s[14:15], 0, v109, s[14:15]
	v_addc_co_u32_e64 v110, s[16:17], 0, v110, s[16:17]
	v_addc_co_u32_e64 v111, s[18:19], 0, v111, s[18:19]
; __device__ __forceinline__ void nsa_mfma_phase(const bf16* z, const bf16* kch, const bf16* kcl, const bf16* vct, const bf16* vst, const bf16* vwt, const float* biasTab, bf16* oc,
;                                                LAS unsigned char* lds, int tid0, int vcu, int G) {
;     ...
;                       if (cnt < 13) bits |= 1u << j; }
.Ltk_done:
	v_cmp_gt_u32_e64 s[10:11], 13, v108
	v_cmp_ne_u32_e64 s[12:13], 0, v112
	v_cmp_ge_i32_e64 s[14:15], s37, v112
	v_lshlrev_b32_e64 v1, v112, 1
	s_and_b64 s[10:11], s[10:11], s[12:13]
	s_and_b64 s[10:11], s[10:11], s[14:15]
	v_cndmask_b32_e64 v1, 0, v1, s[10:11]
	v_or_b32_e32 v58, v58, v1
	v_cmp_gt_u32_e64 s[10:11], 13, v109
	v_cmp_ne_u32_e64 s[12:13], 0, v113
	v_cmp_ge_i32_e64 s[14:15], s37, v113
	v_lshlrev_b32_e64 v1, v113, 1
	s_and_b64 s[10:11], s[10:11], s[12:13]
	s_and_b64 s[10:11], s[10:11], s[14:15]
	v_cndmask_b32_e64 v1, 0, v1, s[10:11]
	v_or_b32_e32 v58, v58, v1
	v_cmp_gt_u32_e64 s[10:11], 13, v110
	v_cmp_ne_u32_e64 s[12:13], 0, v114
	v_cmp_ge_i32_e64 s[14:15], s37, v114
	v_lshlrev_b32_e64 v1, v114, 1
	s_and_b64 s[10:11], s[10:11], s[12:13]
	s_and_b64 s[10:11], s[10:11], s[14:15]
	v_cndmask_b32_e64 v1, 0, v1, s[10:11]
	v_or_b32_e32 v58, v58, v1
	v_cmp_gt_u32_e64 s[10:11], 13, v111
	v_cmp_ne_u32_e64 s[12:13], 0, v115
	v_cmp_ge_i32_e64 s[14:15], s37, v115
	v_lshlrev_b32_e64 v1, v115, 1
	s_and_b64 s[10:11], s[10:11], s[12:13]
	s_and_b64 s[10:11], s[10:11], s[14:15]
	v_cndmask_b32_e64 v1, 0, v1, s[10:11]
	v_or_b32_e32 v58, v58, v1
